# one static s_setprio 1 for waves 4-7 around the hand-written GQA and differential-attention tile loops
# baseline (speedup 1.0000x reference)
.LBB0_1019:
	s_waitcnt vmcnt(1)
	s_nop 7
	v_mbcnt_lo_u32_b32 v80, -1, 0
	v_mbcnt_hi_u32_b32 v80, -1, v80
	v_and_b32_e32 v81, 15, v80
	v_lshlrev_b32_e32 v81, 2, v81
	v_and_b32_e32 v80, 16, v80
	v_cmp_ne_u32_e32 vcc, 0, v80
	ds_bpermute_b32 v82, v81, v248
	ds_bpermute_b32 v81, v81, v249
	s_waitcnt lgkmcnt(0)
	v_cndmask_b32_e32 v80, v82, v81, vcc
	v_add_f32_e32 v80, v64, v80
	v_mul_f32_e32 v133, 0.5, v80
	s_setprio 0

.LBB0_1033:
.LBB0_1034:
	s_or_saveexec_b64 s[4:5], s[12:13]
	v_sub_f32_e32 v204, v201, v143
	v_sub_f32_e32 v205, v202, v143
	s_xor_b64 exec, exec, s[4:5]
	s_cbranch_execz .LBB0_1044
	v_mbcnt_lo_u32_b32 v36, -1, 0
	v_mbcnt_hi_u32_b32 v36, -1, v36
	s_nop 5
	global_load_dwordx4 v[0:3], v[144:145], off
	global_load_dwordx4 v[4:7], v[144:145], off offset:16
	global_load_dwordx4 v[8:11], v[144:145], off offset:64
	global_load_dwordx4 v[12:15], v[144:145], off offset:80
	global_load_dwordx4 v[16:19], v[144:145], off offset:128
	global_load_dwordx4 v[20:23], v[144:145], off offset:144
	global_load_dwordx4 v[24:27], v[144:145], off offset:192
	global_load_dwordx4 v[28:31], v[144:145], off offset:208
	global_load_dwordx4 v[32:35], v[170:171], off offset:128
	v_mov_b32_e32 v175, v177
	v_lshlrev_b32_e32 v38, 2, v36
	v_lshl_add_u64 v[36:37], s[10:11], 0, v[174:175]
	v_xor_b32_e32 v38, 0x80, v38
	v_lshl_add_u64 v[44:45], v[36:37], 0, v[152:153]
	s_waitcnt vmcnt(11)
	ds_bpermute_b32 v48, v38, v96
	v_lshl_add_u64 v[46:47], v[36:37], 0, v[154:155]
	global_load_dwordx4 v[36:39], v[44:45], off
	global_load_dwordx4 v[40:43], v[46:47], off
	s_mov_b32 s0, 0x3e38aa3b
	s_waitcnt lgkmcnt(0)
	v_add_f32_e32 v48, v96, v48
	v_fmamk_f32 v48, v48, 0x3c800000, v221
	v_mul_f32_e32 v49, 0x4b800000, v48
	v_cmp_gt_f32_e32 vcc, s55, v48
	s_barrier
	s_nop 0
	v_cndmask_b32_e32 v48, v48, v49, vcc
	v_rsq_f32_e32 v48, v48
	s_add_i32 s26, s25, s20
	s_ashr_i32 s27, s26, 31
	s_lshl_b64 s[26:27], s[26:27], 14
	v_mul_f32_e32 v49, 0x45800000, v48
	v_cndmask_b32_e32 v48, v48, v49, vcc
	v_lshl_add_u64 v[186:187], v[158:159], 0, s[26:27]
	v_lshl_add_u64 v[188:189], v[160:161], 0, s[26:27]
	s_add_u32 s26, s24, s22
	s_addc_u32 s27, s23, 0
	s_mov_b32 s12, 0
	v_lshl_add_u64 v[190:191], v[162:163], 0, s[26:27]
	s_mov_b32 s13, 0
	s_mov_b32 s27, 0
	s_waitcnt vmcnt(2)
	ds_write_b128 v200, v[32:35]
	s_waitcnt vmcnt(1)
	ds_write_b128 v169, v[36:39] offset:17408
	s_waitcnt vmcnt(0)
	ds_write_b128 v203, v[40:43] offset:17408
	v_pk_mul_f32 v[0:1], v[0:1], v[48:49] op_sel_hi:[1,0]
	v_pk_mul_f32 v[28:29], v[28:29], v[48:49] op_sel_hi:[1,0]
	v_pk_mul_f32 v[0:1], v[0:1], v[94:95]
	v_pk_mul_f32 v[2:3], v[2:3], v[48:49] op_sel_hi:[1,0]
	v_pk_mul_f32 v[0:1], v[0:1], s[0:1] op_sel_hi:[1,0]
	v_pk_mul_f32 v[4:5], v[4:5], v[48:49] op_sel_hi:[1,0]
	v_cvt_pk_bf16_f32 v112, v0, v1
	v_pk_mul_f32 v[0:1], v[28:29], v[66:67]
	v_pk_mul_f32 v[6:7], v[6:7], v[48:49] op_sel_hi:[1,0]
	v_pk_mul_f32 v[0:1], v[0:1], s[0:1] op_sel_hi:[1,0]
	v_pk_mul_f32 v[8:9], v[8:9], v[48:49] op_sel_hi:[1,0]
	v_pk_mul_f32 v[10:11], v[10:11], v[48:49] op_sel_hi:[1,0]
	v_pk_mul_f32 v[12:13], v[12:13], v[48:49] op_sel_hi:[1,0]
	v_pk_mul_f32 v[14:15], v[14:15], v[48:49] op_sel_hi:[1,0]
	v_pk_mul_f32 v[16:17], v[16:17], v[48:49] op_sel_hi:[1,0]
	v_pk_mul_f32 v[18:19], v[18:19], v[48:49] op_sel_hi:[1,0]
	v_pk_mul_f32 v[20:21], v[20:21], v[48:49] op_sel_hi:[1,0]
	v_pk_mul_f32 v[22:23], v[22:23], v[48:49] op_sel_hi:[1,0]
	v_pk_mul_f32 v[24:25], v[24:25], v[48:49] op_sel_hi:[1,0]
	v_pk_mul_f32 v[26:27], v[26:27], v[48:49] op_sel_hi:[1,0]
	v_cvt_pk_bf16_f32 v126, v0, v1
	v_pk_mul_f32 v[0:1], v[30:31], v[48:49] op_sel_hi:[1,0]
	v_pk_mul_f32 v[2:3], v[2:3], v[88:89]
	v_pk_mul_f32 v[4:5], v[4:5], v[82:83]
	v_pk_mul_f32 v[6:7], v[6:7], v[76:77]
	v_pk_mul_f32 v[8:9], v[8:9], v[92:93]
	v_pk_mul_f32 v[10:11], v[10:11], v[86:87]
	v_pk_mul_f32 v[12:13], v[12:13], v[80:81]
	v_pk_mul_f32 v[14:15], v[14:15], v[74:75]
	v_pk_mul_f32 v[16:17], v[16:17], v[90:91]
	v_pk_mul_f32 v[18:19], v[18:19], v[84:85]
	v_pk_mul_f32 v[20:21], v[20:21], v[78:79]
	v_pk_mul_f32 v[22:23], v[22:23], v[72:73]
	v_pk_mul_f32 v[24:25], v[24:25], v[70:71]
	v_pk_mul_f32 v[26:27], v[26:27], v[68:69]
	v_pk_mul_f32 v[0:1], v[0:1], v[64:65]
	v_pk_mul_f32 v[2:3], v[2:3], s[0:1] op_sel_hi:[1,0]
	v_pk_mul_f32 v[4:5], v[4:5], s[0:1] op_sel_hi:[1,0]
	v_pk_mul_f32 v[6:7], v[6:7], s[0:1] op_sel_hi:[1,0]
	v_pk_mul_f32 v[8:9], v[8:9], s[0:1] op_sel_hi:[1,0]
	v_pk_mul_f32 v[10:11], v[10:11], s[0:1] op_sel_hi:[1,0]
	v_pk_mul_f32 v[12:13], v[12:13], s[0:1] op_sel_hi:[1,0]
	v_pk_mul_f32 v[14:15], v[14:15], s[0:1] op_sel_hi:[1,0]
	v_pk_mul_f32 v[16:17], v[16:17], s[0:1] op_sel_hi:[1,0]
	v_pk_mul_f32 v[18:19], v[18:19], s[0:1] op_sel_hi:[1,0]
	v_pk_mul_f32 v[20:21], v[20:21], s[0:1] op_sel_hi:[1,0]
	v_pk_mul_f32 v[22:23], v[22:23], s[0:1] op_sel_hi:[1,0]
	v_pk_mul_f32 v[24:25], v[24:25], s[0:1] op_sel_hi:[1,0]
	v_pk_mul_f32 v[26:27], v[26:27], s[0:1] op_sel_hi:[1,0]
	v_pk_mul_f32 v[0:1], v[0:1], s[0:1] op_sel_hi:[1,0]
	s_mov_b32 s0, 0x60000
	v_cvt_pk_bf16_f32 v127, v0, v1
	v_add_co_u32_e32 v0, vcc, s0, v170
	v_cvt_pk_bf16_f32 v113, v2, v3
	s_nop 0
	v_addc_co_u32_e32 v1, vcc, 0, v171, vcc
	global_load_dwordx4 v[128:131], v[0:1], off offset:128
	global_load_dwordx4 v[132:135], v[44:45], off offset:128
	global_load_dwordx4 v[136:139], v[46:47], off offset:128
	v_mov_b32_e32 v0, 0
	v_cvt_pk_bf16_f32 v114, v4, v5
	v_cvt_pk_bf16_f32 v115, v6, v7
	v_cvt_pk_bf16_f32 v116, v8, v9
	v_cvt_pk_bf16_f32 v117, v10, v11
	v_cvt_pk_bf16_f32 v118, v12, v13
	v_cvt_pk_bf16_f32 v119, v14, v15
	v_cvt_pk_bf16_f32 v120, v16, v17
	v_cvt_pk_bf16_f32 v121, v18, v19
	v_cvt_pk_bf16_f32 v122, v20, v21
	v_cvt_pk_bf16_f32 v123, v22, v23
	v_cvt_pk_bf16_f32 v124, v24, v25
	v_cvt_pk_bf16_f32 v125, v26, v27
	s_mov_b64 s[0:1], 0x60000
	v_mov_b32_e32 v1, v0
	v_mov_b32_e32 v2, v0
	v_mov_b32_e32 v3, v0
	v_mov_b32_e32 v4, v0
	v_mov_b32_e32 v5, v0
	v_mov_b32_e32 v6, v0
	v_mov_b32_e32 v7, v0
	v_mov_b32_e32 v8, v0
	v_mov_b32_e32 v9, v0
	v_mov_b32_e32 v10, v0
	v_mov_b32_e32 v11, v0
	v_mov_b32_e32 v12, v0
	v_mov_b32_e32 v13, v0
	v_mov_b32_e32 v14, v0
	v_mov_b32_e32 v15, v0
	v_mov_b32_e32 v16, v0
	v_mov_b32_e32 v17, v0
	v_mov_b32_e32 v18, v0
	v_mov_b32_e32 v19, v0
	v_mov_b32_e32 v20, v0
	v_mov_b32_e32 v21, v0
	v_mov_b32_e32 v22, v0
	v_mov_b32_e32 v23, v0
	v_mov_b32_e32 v24, v0
	v_mov_b32_e32 v25, v0
	v_mov_b32_e32 v26, v0
	v_mov_b32_e32 v27, v0
	v_mov_b32_e32 v28, v0
	v_mov_b32_e32 v29, v0
	v_mov_b32_e32 v30, v0
	v_mov_b32_e32 v31, v0
	v_mov_b32_e32 v32, v0
	v_mov_b32_e32 v33, v0
	v_mov_b32_e32 v34, v0
	v_mov_b32_e32 v35, v0
	v_mov_b32_e32 v36, v0
	v_mov_b32_e32 v37, v0
	v_mov_b32_e32 v38, v0
	v_mov_b32_e32 v39, v0
	v_mov_b32_e32 v40, v0
	v_mov_b32_e32 v41, v0
	v_mov_b32_e32 v42, v0
	v_mov_b32_e32 v43, v0
	v_mov_b32_e32 v44, v0
	v_mov_b32_e32 v45, v0
	v_mov_b32_e32 v46, v0
	v_mov_b32_e32 v47, v0
	v_mov_b32_e32 v48, v0
	v_mov_b32_e32 v49, v0
	v_mov_b32_e32 v50, v0
	v_mov_b32_e32 v51, v0
	v_mov_b32_e32 v52, v0
	v_mov_b32_e32 v53, v0
	v_mov_b32_e32 v54, v0
	v_mov_b32_e32 v55, v0
	v_mov_b32_e32 v56, v0
	v_mov_b32_e32 v57, v0
	v_mov_b32_e32 v58, v0
	v_mov_b32_e32 v59, v0
	v_mov_b32_e32 v60, v0
	v_mov_b32_e32 v61, v0
	v_mov_b32_e32 v62, v0
	v_mov_b32_e32 v63, v0
	v_mov_b32_e32 v64, v0
	v_mov_b32_e32 v65, v0
	v_mov_b32_e32 v66, v0
	v_mov_b32_e32 v67, v0
	v_mov_b32_e32 v68, v0
	v_mov_b32_e32 v69, v0
	v_mov_b32_e32 v70, v0
	v_mov_b32_e32 v71, v0
	v_mov_b32_e32 v72, v0
	v_mov_b32_e32 v73, v0
	v_mov_b32_e32 v74, v0
	v_mov_b32_e32 v75, v0
	v_mov_b32_e32 v76, v0
	v_mov_b32_e32 v77, v0
	v_mov_b32_e32 v78, v0
	v_mov_b32_e32 v79, v0
	s_waitcnt lgkmcnt(0)
	s_barrier
	v_mbcnt_lo_u32_b32 v248, -1, 0
	v_mbcnt_hi_u32_b32 v248, -1, v248
	v_and_b32_e32 v249, 15, v248
	v_bfe_u32 v248, v248, 4, 1
	v_cmp_eq_u32_e32 vcc, v248, v249
	v_mov_b32_e32 v248, s68
	s_nop 1
	v_cndmask_b32_e32 v226, 0, v248, vcc
	v_cndmask_b32_e32 v227, 0, v248, vcc
	v_cndmask_b32_e32 v228, 0, v248, vcc
	v_cndmask_b32_e32 v229, 0, v248, vcc
	v_mov_b32_e32 v248, 0
	v_mov_b32_e32 v249, 0
	v_mov_b32_e32 v250, 0
	v_mov_b32_e32 v251, 0
	s_cmp_lt_u32 s54, 0x100
	s_cbranch_scc1 .Ldiff_noprio_p1
	s_setprio 1
.Ldiff_noprio_p1:
	s_branch .LBB0_1037

.LBB0_1056:
.LBB0_1057:
	s_andn2_saveexec_b64 s[4:5], s[12:13]
	s_cbranch_execz .LBB0_1020
	v_mbcnt_lo_u32_b32 v36, -1, 0
	v_mbcnt_hi_u32_b32 v36, -1, v36
	s_nop 8
	global_load_dwordx4 v[0:3], v[144:145], off
	global_load_dwordx4 v[4:7], v[144:145], off offset:16
	global_load_dwordx4 v[8:11], v[144:145], off offset:64
	global_load_dwordx4 v[12:15], v[144:145], off offset:80
	global_load_dwordx4 v[16:19], v[144:145], off offset:128
	global_load_dwordx4 v[20:23], v[144:145], off offset:144
	global_load_dwordx4 v[24:27], v[144:145], off offset:192
	global_load_dwordx4 v[28:31], v[144:145], off offset:208
	global_load_dwordx4 v[32:35], v[170:171], off
	v_mov_b32_e32 v175, v177
	v_lshlrev_b32_e32 v38, 2, v36
	v_lshl_add_u64 v[36:37], s[10:11], 0, v[174:175]
	v_xor_b32_e32 v38, 0x80, v38
	v_lshl_add_u64 v[44:45], v[36:37], 0, v[152:153]
	s_waitcnt vmcnt(0)
	ds_bpermute_b32 v48, v38, v96
	v_lshl_add_u64 v[46:47], v[36:37], 0, v[154:155]
	global_load_dwordx4 v[36:39], v[44:45], off
	global_load_dwordx4 v[40:43], v[46:47], off
	s_mov_b32 s0, 0x3e38aa3b
	s_waitcnt lgkmcnt(0)
	v_add_f32_e32 v48, v96, v48
	v_fmamk_f32 v48, v48, 0x3c800000, v221
	v_mul_f32_e32 v49, 0x4b800000, v48
	v_cmp_gt_f32_e32 vcc, s55, v48
	s_barrier
	s_nop 0
	v_cndmask_b32_e32 v48, v48, v49, vcc
	v_rsq_f32_e32 v48, v48
	s_add_i32 s12, s25, s20
	s_ashr_i32 s13, s12, 31
	s_lshl_b64 s[12:13], s[12:13], 14
	v_mul_f32_e32 v49, 0x45800000, v48
	v_cndmask_b32_e32 v48, v48, v49, vcc
	v_lshl_add_u64 v[172:173], v[160:161], 0, s[12:13]
	s_mov_b32 s10, 0
	s_mov_b32 s11, 0
	ds_write_b128 v200, v[32:35]
	s_waitcnt vmcnt(1)
	ds_write_b128 v169, v[36:39] offset:17408
	s_waitcnt vmcnt(0)
	ds_write_b128 v203, v[40:43] offset:17408
	v_pk_mul_f32 v[0:1], v[0:1], v[48:49] op_sel_hi:[1,0]
	v_pk_mul_f32 v[28:29], v[28:29], v[48:49] op_sel_hi:[1,0]
	v_pk_mul_f32 v[0:1], v[0:1], v[68:69]
	v_pk_mul_f32 v[2:3], v[2:3], v[48:49] op_sel_hi:[1,0]
	v_pk_mul_f32 v[0:1], v[0:1], s[0:1] op_sel_hi:[1,0]
	v_pk_mul_f32 v[4:5], v[4:5], v[48:49] op_sel_hi:[1,0]
	v_cvt_pk_bf16_f32 v112, v0, v1
	v_pk_mul_f32 v[0:1], v[28:29], v[66:67]
	v_pk_mul_f32 v[6:7], v[6:7], v[48:49] op_sel_hi:[1,0]
	v_pk_mul_f32 v[0:1], v[0:1], s[0:1] op_sel_hi:[1,0]
	v_pk_mul_f32 v[8:9], v[8:9], v[48:49] op_sel_hi:[1,0]
	v_pk_mul_f32 v[10:11], v[10:11], v[48:49] op_sel_hi:[1,0]
	v_pk_mul_f32 v[12:13], v[12:13], v[48:49] op_sel_hi:[1,0]
	v_pk_mul_f32 v[14:15], v[14:15], v[48:49] op_sel_hi:[1,0]
	v_pk_mul_f32 v[16:17], v[16:17], v[48:49] op_sel_hi:[1,0]
	v_pk_mul_f32 v[18:19], v[18:19], v[48:49] op_sel_hi:[1,0]
	v_pk_mul_f32 v[20:21], v[20:21], v[48:49] op_sel_hi:[1,0]
	v_pk_mul_f32 v[22:23], v[22:23], v[48:49] op_sel_hi:[1,0]
	v_pk_mul_f32 v[24:25], v[24:25], v[48:49] op_sel_hi:[1,0]
	v_pk_mul_f32 v[26:27], v[26:27], v[48:49] op_sel_hi:[1,0]
	v_cvt_pk_bf16_f32 v126, v0, v1
	v_pk_mul_f32 v[0:1], v[30:31], v[48:49] op_sel_hi:[1,0]
	v_pk_mul_f32 v[2:3], v[2:3], v[70:71]
	v_pk_mul_f32 v[4:5], v[4:5], v[72:73]
	v_pk_mul_f32 v[6:7], v[6:7], v[74:75]
	v_pk_mul_f32 v[8:9], v[8:9], v[80:81]
	v_pk_mul_f32 v[10:11], v[10:11], v[82:83]
	v_pk_mul_f32 v[12:13], v[12:13], v[84:85]
	v_pk_mul_f32 v[14:15], v[14:15], v[86:87]
	v_pk_mul_f32 v[16:17], v[16:17], v[88:89]
	v_pk_mul_f32 v[18:19], v[18:19], v[90:91]
	v_pk_mul_f32 v[20:21], v[20:21], v[92:93]
	v_pk_mul_f32 v[22:23], v[22:23], v[94:95]
	v_pk_mul_f32 v[24:25], v[24:25], v[78:79]
	v_pk_mul_f32 v[26:27], v[26:27], v[76:77]
	v_pk_mul_f32 v[0:1], v[0:1], v[64:65]
	v_pk_mul_f32 v[2:3], v[2:3], s[0:1] op_sel_hi:[1,0]
	v_pk_mul_f32 v[4:5], v[4:5], s[0:1] op_sel_hi:[1,0]
	v_pk_mul_f32 v[6:7], v[6:7], s[0:1] op_sel_hi:[1,0]
	v_pk_mul_f32 v[8:9], v[8:9], s[0:1] op_sel_hi:[1,0]
	v_pk_mul_f32 v[10:11], v[10:11], s[0:1] op_sel_hi:[1,0]
	v_pk_mul_f32 v[12:13], v[12:13], s[0:1] op_sel_hi:[1,0]
	v_pk_mul_f32 v[14:15], v[14:15], s[0:1] op_sel_hi:[1,0]
	v_pk_mul_f32 v[16:17], v[16:17], s[0:1] op_sel_hi:[1,0]
	v_pk_mul_f32 v[18:19], v[18:19], s[0:1] op_sel_hi:[1,0]
	v_pk_mul_f32 v[20:21], v[20:21], s[0:1] op_sel_hi:[1,0]
	v_pk_mul_f32 v[22:23], v[22:23], s[0:1] op_sel_hi:[1,0]
	v_pk_mul_f32 v[24:25], v[24:25], s[0:1] op_sel_hi:[1,0]
	v_pk_mul_f32 v[26:27], v[26:27], s[0:1] op_sel_hi:[1,0]
	v_pk_mul_f32 v[0:1], v[0:1], s[0:1] op_sel_hi:[1,0]
	s_mov_b32 s0, 0x60000
	v_cvt_pk_bf16_f32 v127, v0, v1
	v_add_co_u32_e32 v0, vcc, s0, v170
	v_cvt_pk_bf16_f32 v113, v2, v3
	s_nop 0
	v_addc_co_u32_e32 v1, vcc, 0, v171, vcc
	global_load_dwordx4 v[128:131], v[0:1], off
	global_load_dwordx4 v[132:135], v[44:45], off offset:128
	global_load_dwordx4 v[136:139], v[46:47], off offset:128
	v_lshl_add_u64 v[170:171], v[158:159], 0, s[12:13]
	s_add_u32 s12, s24, s22
	s_addc_u32 s13, s23, 0
	v_mov_b32_e32 v0, 0
	v_cvt_pk_bf16_f32 v114, v4, v5
	v_cvt_pk_bf16_f32 v115, v6, v7
	v_cvt_pk_bf16_f32 v116, v8, v9
	v_cvt_pk_bf16_f32 v117, v10, v11
	v_cvt_pk_bf16_f32 v118, v12, v13
	v_cvt_pk_bf16_f32 v119, v14, v15
	v_cvt_pk_bf16_f32 v120, v16, v17
	v_cvt_pk_bf16_f32 v121, v18, v19
	v_cvt_pk_bf16_f32 v122, v20, v21
	v_cvt_pk_bf16_f32 v123, v22, v23
	v_cvt_pk_bf16_f32 v124, v24, v25
	v_cvt_pk_bf16_f32 v125, v26, v27
	s_mov_b64 s[0:1], 0x60000
	v_lshl_add_u64 v[174:175], v[164:165], 0, s[12:13]
	s_mov_b32 s13, 0
	v_mov_b32_e32 v1, v0
	v_mov_b32_e32 v2, v0
	v_mov_b32_e32 v3, v0
	v_mov_b32_e32 v4, v0
	v_mov_b32_e32 v5, v0
	v_mov_b32_e32 v6, v0
	v_mov_b32_e32 v7, v0
	v_mov_b32_e32 v8, v0
	v_mov_b32_e32 v9, v0
	v_mov_b32_e32 v10, v0
	v_mov_b32_e32 v11, v0
	v_mov_b32_e32 v12, v0
	v_mov_b32_e32 v13, v0
	v_mov_b32_e32 v14, v0
	v_mov_b32_e32 v15, v0
	v_mov_b32_e32 v16, v0
	v_mov_b32_e32 v17, v0
	v_mov_b32_e32 v18, v0
	v_mov_b32_e32 v19, v0
	v_mov_b32_e32 v20, v0
	v_mov_b32_e32 v21, v0
	v_mov_b32_e32 v22, v0
	v_mov_b32_e32 v23, v0
	v_mov_b32_e32 v24, v0
	v_mov_b32_e32 v25, v0
	v_mov_b32_e32 v26, v0
	v_mov_b32_e32 v27, v0
	v_mov_b32_e32 v28, v0
	v_mov_b32_e32 v29, v0
	v_mov_b32_e32 v30, v0
	v_mov_b32_e32 v31, v0
	v_mov_b32_e32 v32, v0
	v_mov_b32_e32 v33, v0
	v_mov_b32_e32 v34, v0
	v_mov_b32_e32 v35, v0
	v_mov_b32_e32 v36, v0
	v_mov_b32_e32 v37, v0
	v_mov_b32_e32 v38, v0
	v_mov_b32_e32 v39, v0
	v_mov_b32_e32 v40, v0
	v_mov_b32_e32 v41, v0
	v_mov_b32_e32 v42, v0
	v_mov_b32_e32 v43, v0
	v_mov_b32_e32 v44, v0
	v_mov_b32_e32 v45, v0
	v_mov_b32_e32 v46, v0
	v_mov_b32_e32 v47, v0
	v_mov_b32_e32 v48, v0
	v_mov_b32_e32 v49, v0
	v_mov_b32_e32 v50, v0
	v_mov_b32_e32 v51, v0
	v_mov_b32_e32 v52, v0
	v_mov_b32_e32 v53, v0
	v_mov_b32_e32 v54, v0
	v_mov_b32_e32 v55, v0
	v_mov_b32_e32 v56, v0
	v_mov_b32_e32 v57, v0
	v_mov_b32_e32 v58, v0
	v_mov_b32_e32 v59, v0
	v_mov_b32_e32 v60, v0
	v_mov_b32_e32 v61, v0
	v_mov_b32_e32 v62, v0
	v_mov_b32_e32 v63, v0
	v_mov_b32_e32 v64, v0
	v_mov_b32_e32 v65, v0
	v_mov_b32_e32 v66, v0
	v_mov_b32_e32 v67, v0
	v_mov_b32_e32 v68, v0
	v_mov_b32_e32 v69, v0
	v_mov_b32_e32 v70, v0
	v_mov_b32_e32 v71, v0
	v_mov_b32_e32 v72, v0
	v_mov_b32_e32 v73, v0
	v_mov_b32_e32 v74, v0
	v_mov_b32_e32 v75, v0
	v_mov_b32_e32 v76, v0
	v_mov_b32_e32 v77, v0
	v_mov_b32_e32 v78, v0
	v_mov_b32_e32 v79, v0
	s_waitcnt lgkmcnt(0)
	s_barrier
	v_mbcnt_lo_u32_b32 v248, -1, 0
	v_mbcnt_hi_u32_b32 v248, -1, v248
	v_and_b32_e32 v249, 15, v248
	v_bfe_u32 v248, v248, 4, 1
	v_cmp_eq_u32_e32 vcc, v248, v249
	v_mov_b32_e32 v248, s68
	s_nop 1
	v_cndmask_b32_e32 v226, 0, v248, vcc
	v_cndmask_b32_e32 v227, 0, v248, vcc
	v_cndmask_b32_e32 v228, 0, v248, vcc
	v_cndmask_b32_e32 v229, 0, v248, vcc
	v_mov_b32_e32 v248, 0
	v_mov_b32_e32 v249, 0
	v_mov_b32_e32 v250, 0
	v_mov_b32_e32 v251, 0
	s_cmp_lt_u32 s54, 0x100
	s_cbranch_scc1 .Ldiff_noprio_p2
	s_setprio 1

.LBB0_1248:
	s_cmp_lt_u32 s54, 0x100
	s_cbranch_scc1 .Lgqa_noprio
	s_setprio 1

.Lgqa_last:
	v_mfma_f32_16x16x32_bf16 v[96:99], v[244:247], v[80:83], v[96:99]
	v_exp_f32_e32 v88, v88
	v_exp_f32_e32 v89, v89
	v_exp_f32_e32 v90, v90
	v_mfma_f32_32x32x16_bf16 v[0:15], v[226:229], v[80:83], v[0:15]
	v_exp_f32_e32 v91, v91
	v_exp_f32_e32 v92, v92
	v_exp_f32_e32 v93, v93
	v_cvt_pk_bf16_f32 v88, v88, v89
	v_mfma_f32_32x32x16_bf16 v[16:31], v[230:233], v[80:83], v[16:31]
	v_exp_f32_e32 v94, v94
	v_exp_f32_e32 v95, v95
	v_cvt_pk_bf16_f32 v89, v90, v91
	v_cvt_pk_bf16_f32 v90, v92, v93
	v_cvt_pk_bf16_f32 v91, v94, v95
	s_nop 1
	v_mfma_f32_16x16x32_bf16 v[96:99], v[244:247], v[88:91], v[96:99]
	s_waitcnt lgkmcnt(1)
	v_mfma_f32_32x32x16_bf16 v[0:15], v[236:239], v[88:91], v[0:15]
	s_waitcnt lgkmcnt(0)
	v_mfma_f32_32x32x16_bf16 v[16:31], v[240:243], v[88:91], v[16:31]
	v_mbcnt_lo_u32_b32 v249, -1, 0
	v_mbcnt_hi_u32_b32 v249, -1, v249
	v_and_b32_e32 v250, 15, v249
	v_lshlrev_b32_e32 v250, 2, v250
	v_and_b32_e32 v249, 16, v249
	s_nop 3
	v_cmp_ne_u32_e32 vcc, 0, v249
	ds_bpermute_b32 v248, v250, v96
	ds_bpermute_b32 v250, v250, v97
	s_waitcnt lgkmcnt(0)
	v_cndmask_b32_e32 v96, v248, v250, vcc
	s_setprio 0
	s_branch .LBB0_1232
